# grid barrier: every block waits on the global generation word directly (one hop less), the per-XCD generation bump is dropped
# speedup vs baseline: 1.0274x; 1.0274x over previous
.LBB0_218:
	s_or_b64 exec, exec, s[2:3]
	v_cvt_f32_u32_e32 v4, v2
	s_waitcnt vmcnt(0)
	v_readfirstlane_b32 s2, v3
	v_sub_u32_e32 v3, 0, v2
	v_rcp_iflag_f32_e32 v4, v4
	v_add_u32_e32 v5, s2, v1
	v_mul_f32_e32 v4, 0x4f7ffffe, v4
	v_cvt_u32_f32_e32 v4, v4
	v_mul_lo_u32 v1, v3, v4
	v_mul_hi_u32 v1, v4, v1
	v_add_u32_e32 v1, v4, v1
	v_mul_hi_u32 v1, v5, v1
	v_mul_lo_u32 v3, v1, v2
	v_sub_u32_e32 v3, v5, v3
	v_add_u32_e32 v4, 1, v1
	v_cmp_ge_u32_e32 vcc, v3, v2
	s_nop 1
	v_cndmask_b32_e32 v1, v1, v4, vcc
	v_sub_u32_e32 v4, v3, v2
	v_cndmask_b32_e32 v3, v3, v4, vcc
	v_add_u32_e32 v4, 1, v1
	v_cmp_ge_u32_e32 vcc, v3, v2
	v_add_u32_e32 v3, 1, v5
	s_nop 0
	v_cndmask_b32_e32 v1, v1, v4, vcc
	v_mul_lo_u32 v4, v2, v1
	v_add_u32_e32 v2, v4, v2
	v_cmp_ne_u32_e32 vcc, v3, v2
	s_and_saveexec_b64 s[2:3], vcc
	s_xor_b64 s[2:3], exec, s[2:3]
	s_cbranch_execz .LBB0_232
	s_mov_b32 s6, s22
	s_waitcnt lgkmcnt(0)
	v_mov_b32_e32 v0, 0
	s_mov_b32 s7, s23
	s_nop 4
	global_load_dword v2, v0, s[6:7] sc1
	s_waitcnt vmcnt(0)
	v_cmp_eq_u32_e32 vcc, v2, v1
	s_and_saveexec_b64 s[6:7], vcc
	s_cbranch_execz .LBB0_231
	s_mov_b32 s19, 1
	s_mov_b64 s[8:9], 0
	s_branch .LBB0_222

.LBB0_226:
	s_mov_b32 s12, s22
	s_mov_b32 s13, s23
	s_add_i32 s19, s19, 1
	s_mov_b64 s[14:15], -1
	s_nop 2
	global_load_dword v2, v0, s[12:13] sc1
	s_waitcnt vmcnt(0)
	v_cmp_ne_u32_e32 vcc, v2, v1
	s_orn2_b64 s[12:13], vcc, exec
	s_branch .LBB0_221

.LBB0_249:
	s_or_b64 exec, exec, s[2:3]
	s_mov_b64 s[2:3], exec
	v_mbcnt_lo_u32_b32 v0, s2, 0
	v_mbcnt_hi_u32_b32 v0, s3, v0
	v_cmp_eq_u32_e32 vcc, 0, v0
	s_waitcnt vmcnt(0)
	buffer_inv sc1
	s_and_saveexec_b64 s[6:7], vcc
	s_cbranch_execz .LBB0_251
	s_bcnt1_i32_b64 s2, s[2:3]
	v_mov_b32_e32 v1, s2
	v_readlane_b32 s2, v236, 32
	v_mov_b32_e32 v0, 0
	v_readlane_b32 s3, v236, 33
	s_nop 4
	s_nop 0

.LBB0_292:
	s_or_b64 exec, exec, s[12:13]
	v_cvt_f32_u32_e32 v5, v2
	s_waitcnt vmcnt(0)
	v_readfirstlane_b32 s12, v4
	v_sub_u32_e32 v4, 0, v2
	v_rcp_iflag_f32_e32 v5, v5
	v_add_u32_e32 v6, s12, v1
	v_mul_f32_e32 v5, 0x4f7ffffe, v5
	v_cvt_u32_f32_e32 v5, v5
	v_mul_lo_u32 v1, v4, v5
	v_mul_hi_u32 v1, v5, v1
	v_add_u32_e32 v1, v5, v1
	v_mul_hi_u32 v1, v6, v1
	v_mul_lo_u32 v4, v1, v2
	v_sub_u32_e32 v4, v6, v4
	v_add_u32_e32 v5, 1, v1
	v_cmp_ge_u32_e32 vcc, v4, v2
	s_nop 1
	v_cndmask_b32_e32 v1, v1, v5, vcc
	v_sub_u32_e32 v5, v4, v2
	v_cndmask_b32_e32 v4, v4, v5, vcc
	v_add_u32_e32 v5, 1, v1
	v_cmp_ge_u32_e32 vcc, v4, v2
	v_add_u32_e32 v4, 1, v6
	s_nop 0
	v_cndmask_b32_e32 v1, v1, v5, vcc
	v_mul_lo_u32 v5, v2, v1
	v_add_u32_e32 v2, v5, v2
	v_cmp_ne_u32_e32 vcc, v4, v2
	s_and_saveexec_b64 s[12:13], vcc
	s_xor_b64 s[12:13], exec, s[12:13]
	s_cbranch_execz .LBB0_306
	v_readlane_b32 s40, v236, 36
	v_readlane_b32 s41, v236, 37
	s_waitcnt lgkmcnt(0)
	s_nop 3
	global_load_dword v0, v3, s[40:41] sc1
	s_waitcnt vmcnt(0)
	v_cmp_eq_u32_e32 vcc, v0, v1
	s_and_saveexec_b64 s[40:41], vcc
	s_cbranch_execz .LBB0_305
	s_mov_b32 s15, 1
	s_mov_b64 s[42:43], 0
	s_branch .LBB0_296

.LBB0_300:
	v_readlane_b32 s46, v236, 36
	v_readlane_b32 s47, v236, 37
	s_add_i32 s15, s15, 1
	s_mov_b64 s[48:49], -1
	s_nop 2
	global_load_dword v0, v3, s[46:47] sc1
	s_waitcnt vmcnt(0)
	v_cmp_ne_u32_e32 vcc, v0, v1
	s_orn2_b64 s[46:47], vcc, exec
	s_branch .LBB0_295

.LBB0_323:
	s_or_b64 exec, exec, s[12:13]
	s_mov_b64 s[12:13], exec
	v_mbcnt_lo_u32_b32 v0, s12, 0
	v_mbcnt_hi_u32_b32 v0, s13, v0
	v_cmp_eq_u32_e32 vcc, 0, v0
	s_waitcnt vmcnt(0)
	buffer_inv sc1
	s_and_saveexec_b64 s[40:41], vcc
	s_cbranch_execz .LBB0_325
	s_bcnt1_i32_b64 s12, s[12:13]
	v_mov_b32_e32 v0, s12
	v_readlane_b32 s12, v236, 32
	v_readlane_b32 s13, v236, 33
	s_nop 4
	s_nop 0

.LBB0_499:
	s_or_b64 exec, exec, s[12:13]
	v_cvt_f32_u32_e32 v5, v2
	s_waitcnt vmcnt(0)
	v_readfirstlane_b32 s12, v4
	v_sub_u32_e32 v4, 0, v2
	v_rcp_iflag_f32_e32 v5, v5
	v_add_u32_e32 v6, s12, v1
	v_mul_f32_e32 v5, 0x4f7ffffe, v5
	v_cvt_u32_f32_e32 v5, v5
	v_mul_lo_u32 v1, v4, v5
	v_mul_hi_u32 v1, v5, v1
	v_add_u32_e32 v1, v5, v1
	v_mul_hi_u32 v1, v6, v1
	v_mul_lo_u32 v4, v1, v2
	v_sub_u32_e32 v4, v6, v4
	v_add_u32_e32 v5, 1, v1
	v_cmp_ge_u32_e32 vcc, v4, v2
	s_nop 1
	v_cndmask_b32_e32 v1, v1, v5, vcc
	v_sub_u32_e32 v5, v4, v2
	v_cndmask_b32_e32 v4, v4, v5, vcc
	v_add_u32_e32 v5, 1, v1
	v_cmp_ge_u32_e32 vcc, v4, v2
	v_add_u32_e32 v4, 1, v6
	s_nop 0
	v_cndmask_b32_e32 v1, v1, v5, vcc
	v_mul_lo_u32 v5, v2, v1
	v_add_u32_e32 v2, v5, v2
	v_cmp_ne_u32_e32 vcc, v4, v2
	s_and_saveexec_b64 s[12:13], vcc
	s_xor_b64 s[12:13], exec, s[12:13]
	s_cbranch_execz .LBB0_513
	v_readlane_b32 s40, v236, 36
	v_readlane_b32 s41, v236, 37
	s_waitcnt lgkmcnt(0)
	s_nop 3
	global_load_dword v0, v3, s[40:41] sc1
	s_waitcnt vmcnt(0)
	v_cmp_eq_u32_e32 vcc, v0, v1
	s_and_saveexec_b64 s[40:41], vcc
	s_cbranch_execz .LBB0_512
	s_mov_b32 s34, 1
	s_mov_b64 s[42:43], 0
	s_branch .LBB0_503

.LBB0_507:
	v_readlane_b32 s46, v236, 36
	v_readlane_b32 s47, v236, 37
	s_add_i32 s34, s34, 1
	s_mov_b64 s[48:49], -1
	s_nop 2
	global_load_dword v0, v3, s[46:47] sc1
	s_waitcnt vmcnt(0)
	v_cmp_ne_u32_e32 vcc, v0, v1
	s_orn2_b64 s[46:47], vcc, exec
	s_branch .LBB0_502

.LBB0_1081:
	s_or_b64 exec, exec, s[2:3]
	v_cvt_f32_u32_e32 v4, v2
	s_waitcnt vmcnt(0)
	v_readfirstlane_b32 s2, v3
	v_sub_u32_e32 v3, 0, v2
	v_rcp_iflag_f32_e32 v4, v4
	v_add_u32_e32 v5, s2, v1
	v_mul_f32_e32 v4, 0x4f7ffffe, v4
	v_cvt_u32_f32_e32 v4, v4
	v_mul_lo_u32 v1, v3, v4
	v_mul_hi_u32 v1, v4, v1
	v_add_u32_e32 v1, v4, v1
	v_mul_hi_u32 v1, v5, v1
	v_mul_lo_u32 v3, v1, v2
	v_sub_u32_e32 v3, v5, v3
	v_add_u32_e32 v4, 1, v1
	v_cmp_ge_u32_e32 vcc, v3, v2
	s_nop 1
	v_cndmask_b32_e32 v1, v1, v4, vcc
	v_sub_u32_e32 v4, v3, v2
	v_cndmask_b32_e32 v3, v3, v4, vcc
	v_add_u32_e32 v4, 1, v1
	v_cmp_ge_u32_e32 vcc, v3, v2
	v_add_u32_e32 v3, 1, v5
	s_nop 0
	v_cndmask_b32_e32 v1, v1, v4, vcc
	v_mul_lo_u32 v4, v2, v1
	v_add_u32_e32 v2, v4, v2
	v_cmp_ne_u32_e32 vcc, v3, v2
	s_and_saveexec_b64 s[2:3], vcc
	s_xor_b64 s[2:3], exec, s[2:3]
	s_cbranch_execz .LBB0_1095
	v_readlane_b32 s4, v236, 36
	s_waitcnt lgkmcnt(0)
	v_mov_b32_e32 v0, 0
	v_readlane_b32 s5, v236, 37
	s_nop 4
	global_load_dword v2, v0, s[4:5] sc1
	s_waitcnt vmcnt(0)
	v_cmp_eq_u32_e32 vcc, v2, v1
	s_and_saveexec_b64 s[4:5], vcc
	s_cbranch_execz .LBB0_1094
	s_mov_b32 s16, 1
	s_mov_b64 s[6:7], 0
	s_branch .LBB0_1085

.LBB0_1089:
	v_readlane_b32 s10, v236, 36
	v_readlane_b32 s11, v236, 37
	s_add_i32 s16, s16, 1
	s_mov_b64 s[12:13], -1
	s_nop 2
	global_load_dword v2, v0, s[10:11] sc1
	s_waitcnt vmcnt(0)
	v_cmp_ne_u32_e32 vcc, v2, v1
	s_orn2_b64 s[10:11], vcc, exec
	s_branch .LBB0_1084

.LBB0_1112:
	s_or_b64 exec, exec, s[2:3]
	s_mov_b64 s[2:3], exec
	v_mbcnt_lo_u32_b32 v0, s2, 0
	v_mbcnt_hi_u32_b32 v0, s3, v0
	v_cmp_eq_u32_e32 vcc, 0, v0
	s_waitcnt vmcnt(0)
	buffer_inv sc1
	s_and_saveexec_b64 s[4:5], vcc
	s_cbranch_execz .LBB0_1114
	s_bcnt1_i32_b64 s2, s[2:3]
	v_mov_b32_e32 v1, s2
	v_readlane_b32 s2, v236, 32
	v_mov_b32_e32 v0, 0
	v_readlane_b32 s3, v236, 33
	s_nop 4
	s_nop 0
